# v054 + grid barrier: the first arriver of each XCC also starts an L2 write-back (not waited for) ahead of the last arriver's fence
# baseline (speedup 1.0000x reference)
.LBB0_262:
	s_load_dwordx2 s[6:7], s[0:1], 0x150
	v_readlane_b32 s4, v251, 38
	s_or_b32 s4, s4, 2
	s_waitcnt lgkmcnt(0)
	s_cmp_ge_i32 s4, s7
	s_cbranch_scc1 .LBB0_312
	s_waitcnt vmcnt(0)
	s_barrier
	s_mov_b64 s[16:17], exec
	v_readlane_b32 s6, v251, 22
	v_readlane_b32 s7, v251, 23
	s_and_b64 s[6:7], s[16:17], s[6:7]
	s_mov_b64 exec, s[6:7]
	s_cbranch_execz .LBB0_311
	s_waitcnt vmcnt(0) lgkmcnt(0)
	v_mov_b32_e32 v2, 0x22020
	ds_read_b64 v[4:5], v2
	v_readlane_b32 s6, v252, 35
	v_readlane_b32 s7, v252, 36
	v_readlane_b32 s8, v252, 39
	v_readlane_b32 s9, v252, 40
	v_mov_b32_e32 v6, 1
	s_nop 4
	global_atomic_add v6, v3, v6, s[6:7] sc0
	s_waitcnt vmcnt(0) lgkmcnt(0)
	v_cvt_f32_u32_e32 v7, v6
	v_cvt_f32_u32_e32 v8, v4
	v_add_f32_e32 v7, 0.5, v7
	v_rcp_f32_e32 v8, v8
	s_nop 1
	v_mul_f32_e32 v7, v7, v8
	v_cvt_u32_f32_e32 v7, v7
	v_mad_u32_u24 v8, v7, v4, v4
	v_mad_u32_u24 v9, v7, v5, v5
	v_sub_u32_e32 v2, v8, v4
	v_cmp_ne_u32_e32 vcc, v6, v2
	s_cbranch_vccnz .Lxb_nf_0
	buffer_wbl2 sc1
.Lxb_nf_0:
	v_add_u32_e32 v6, 1, v6
	v_cmp_eq_u32_e32 vcc, v6, v8
	s_cbranch_vccz .Lxb_poll_0
	buffer_wbl2 sc1
	s_waitcnt vmcnt(0)
	v_mov_b32_e32 v6, 1
	global_atomic_add v3, v6, s[8:9]

.LBB0_828:
	s_load_dwordx2 s[6:7], s[0:1], 0x150
	v_readlane_b32 s4, v251, 38
	s_or_b32 s4, s4, 3
	s_waitcnt lgkmcnt(0)
	s_cmp_ge_i32 s4, s7
	s_cbranch_scc1 .LBB0_878
	s_waitcnt vmcnt(0)
	s_waitcnt vmcnt(0)
	s_barrier
	s_mov_b64 s[16:17], exec
	v_readlane_b32 s6, v251, 22
	v_readlane_b32 s7, v251, 23
	s_and_b64 s[6:7], s[16:17], s[6:7]
	s_mov_b64 exec, s[6:7]
	s_cbranch_execz .LBB0_877
	s_waitcnt vmcnt(0) lgkmcnt(0)
	v_mov_b32_e32 v2, 0x22020
	ds_read_b64 v[4:5], v2
	v_readlane_b32 s6, v252, 35
	v_readlane_b32 s7, v252, 36
	v_readlane_b32 s8, v252, 39
	v_readlane_b32 s9, v252, 40
	v_mov_b32_e32 v6, 1
	s_nop 4
	global_atomic_add v6, v3, v6, s[6:7] sc0
	s_waitcnt vmcnt(0) lgkmcnt(0)
	v_cvt_f32_u32_e32 v7, v6
	v_cvt_f32_u32_e32 v8, v4
	v_add_f32_e32 v7, 0.5, v7
	v_rcp_f32_e32 v8, v8
	s_nop 1
	v_mul_f32_e32 v7, v7, v8
	v_cvt_u32_f32_e32 v7, v7
	v_mad_u32_u24 v8, v7, v4, v4
	v_mad_u32_u24 v9, v7, v5, v5
	v_sub_u32_e32 v2, v8, v4
	v_cmp_ne_u32_e32 vcc, v6, v2
	s_cbranch_vccnz .Lxb_nf_1
	buffer_wbl2 sc1

.LBB0_1216:
	s_load_dwordx2 s[6:7], s[0:1], 0x150
	v_readlane_b32 s4, v251, 38
	s_add_i32 s4, s4, 4
	s_waitcnt lgkmcnt(0)
	s_cmp_ge_i32 s4, s7
	s_cbranch_scc1 .LBB0_1266
	s_waitcnt vmcnt(0)
	s_waitcnt vmcnt(63) expcnt(7) lgkmcnt(15)
	s_barrier
	s_mov_b64 s[16:17], exec
	v_readlane_b32 s6, v251, 22
	v_readlane_b32 s7, v251, 23
	s_and_b64 s[6:7], s[16:17], s[6:7]
	s_mov_b64 exec, s[6:7]
	s_cbranch_execz .LBB0_1265
	s_waitcnt vmcnt(0) lgkmcnt(0)
	v_mov_b32_e32 v2, 0x22020
	ds_read_b64 v[4:5], v2
	v_readlane_b32 s6, v252, 35
	v_readlane_b32 s7, v252, 36
	v_readlane_b32 s8, v252, 39
	v_readlane_b32 s9, v252, 40
	v_mov_b32_e32 v6, 1
	s_nop 4
	global_atomic_add v6, v3, v6, s[6:7] sc0
	s_waitcnt vmcnt(0) lgkmcnt(0)
	v_cvt_f32_u32_e32 v7, v6
	v_cvt_f32_u32_e32 v8, v4
	v_add_f32_e32 v7, 0.5, v7
	v_rcp_f32_e32 v8, v8
	s_nop 1
	v_mul_f32_e32 v7, v7, v8
	v_cvt_u32_f32_e32 v7, v7
	v_mad_u32_u24 v8, v7, v4, v4
	v_mad_u32_u24 v9, v7, v5, v5
	v_sub_u32_e32 v2, v8, v4
	v_cmp_ne_u32_e32 vcc, v6, v2
	s_cbranch_vccnz .Lxb_nf_2
	buffer_wbl2 sc1

.LBB0_1281:
	s_or_b64 exec, exec, s[16:17]
	s_load_dwordx2 s[6:7], s[0:1], 0x150
	v_readlane_b32 s4, v251, 38
	s_add_i32 s4, s4, 5
	s_waitcnt lgkmcnt(0)
	s_cmp_ge_i32 s4, s7
	s_cbranch_scc1 .LBB0_1331
	s_waitcnt vmcnt(0)
	s_barrier
	s_mov_b64 s[16:17], exec
	v_readlane_b32 s6, v251, 22
	v_readlane_b32 s7, v251, 23
	s_and_b64 s[6:7], s[16:17], s[6:7]
	s_mov_b64 exec, s[6:7]
	s_cbranch_execz .LBB0_1330
	s_waitcnt vmcnt(0) lgkmcnt(0)
	v_mov_b32_e32 v2, 0x22020
	ds_read_b64 v[4:5], v2
	v_readlane_b32 s6, v252, 35
	v_readlane_b32 s7, v252, 36
	v_readlane_b32 s8, v252, 39
	v_readlane_b32 s9, v252, 40
	v_mov_b32_e32 v6, 1
	s_nop 4
	global_atomic_add v6, v3, v6, s[6:7] sc0
	s_waitcnt vmcnt(0) lgkmcnt(0)
	v_cvt_f32_u32_e32 v7, v6
	v_cvt_f32_u32_e32 v8, v4
	v_add_f32_e32 v7, 0.5, v7
	v_rcp_f32_e32 v8, v8
	s_nop 1
	v_mul_f32_e32 v7, v7, v8
	v_cvt_u32_f32_e32 v7, v7
	v_mad_u32_u24 v8, v7, v4, v4
	v_mad_u32_u24 v9, v7, v5, v5
	v_sub_u32_e32 v2, v8, v4
	v_cmp_ne_u32_e32 vcc, v6, v2
	s_cbranch_vccnz .Lxb_nf_3
	buffer_wbl2 sc1

.LBB0_1598:
	s_load_dwordx2 s[6:7], s[0:1], 0x150
	v_readlane_b32 s4, v251, 38
	s_add_i32 s4, s4, 6
	s_waitcnt lgkmcnt(0)
	s_cmp_ge_i32 s4, s7
	s_cbranch_scc1 .LBB0_1648
	s_waitcnt vmcnt(0)
	s_barrier
	s_mov_b64 s[16:17], exec
	v_readlane_b32 s6, v251, 22
	v_readlane_b32 s7, v251, 23
	s_and_b64 s[6:7], s[16:17], s[6:7]
	s_mov_b64 exec, s[6:7]
	s_cbranch_execz .LBB0_1647
	s_waitcnt vmcnt(0) lgkmcnt(0)
	v_mov_b32_e32 v2, 0x22020
	ds_read_b64 v[4:5], v2
	v_readlane_b32 s6, v252, 35
	v_readlane_b32 s7, v252, 36
	v_readlane_b32 s8, v252, 39
	v_readlane_b32 s9, v252, 40
	v_mov_b32_e32 v6, 1
	s_nop 4
	global_atomic_add v6, v3, v6, s[6:7] sc0
	s_waitcnt vmcnt(0) lgkmcnt(0)
	v_cvt_f32_u32_e32 v7, v6
	v_cvt_f32_u32_e32 v8, v4
	v_add_f32_e32 v7, 0.5, v7
	v_rcp_f32_e32 v8, v8
	s_nop 1
	v_mul_f32_e32 v7, v7, v8
	v_cvt_u32_f32_e32 v7, v7
	v_mad_u32_u24 v8, v7, v4, v4
	v_mad_u32_u24 v9, v7, v5, v5
	v_sub_u32_e32 v2, v8, v4
	v_cmp_ne_u32_e32 vcc, v6, v2
	s_cbranch_vccnz .Lxb_nf_4
	buffer_wbl2 sc1

.LBB0_1682:
	s_load_dwordx2 s[6:7], s[0:1], 0x150
	v_readlane_b32 s4, v251, 38
	s_add_i32 s4, s4, 7
	s_waitcnt lgkmcnt(0)
	s_barrier
	s_cmp_ge_i32 s4, s7
	s_cbranch_scc1 .LBB0_1732
	s_waitcnt vmcnt(0)
	s_barrier
	s_mov_b64 s[16:17], exec
	v_readlane_b32 s6, v251, 22
	v_readlane_b32 s7, v251, 23
	s_and_b64 s[6:7], s[16:17], s[6:7]
	s_mov_b64 exec, s[6:7]
	s_cbranch_execz .LBB0_1731
	s_waitcnt vmcnt(0) lgkmcnt(0)
	v_mov_b32_e32 v2, 0x22020
	ds_read_b64 v[4:5], v2
	v_readlane_b32 s6, v252, 35
	v_readlane_b32 s7, v252, 36
	v_readlane_b32 s8, v252, 39
	v_readlane_b32 s9, v252, 40
	v_mov_b32_e32 v6, 1
	s_nop 4
	global_atomic_add v6, v3, v6, s[6:7] sc0
	s_waitcnt vmcnt(0) lgkmcnt(0)
	v_cvt_f32_u32_e32 v7, v6
	v_cvt_f32_u32_e32 v8, v4
	v_add_f32_e32 v7, 0.5, v7
	v_rcp_f32_e32 v8, v8
	s_nop 1
	v_mul_f32_e32 v7, v7, v8
	v_cvt_u32_f32_e32 v7, v7
	v_mad_u32_u24 v8, v7, v4, v4
	v_mad_u32_u24 v9, v7, v5, v5
	v_sub_u32_e32 v2, v8, v4
	v_cmp_ne_u32_e32 vcc, v6, v2
	s_cbranch_vccnz .Lxb_nf_5
	buffer_wbl2 sc1

.LBB0_2054:
	s_load_dwordx2 s[6:7], s[0:1], 0x150
	v_readlane_b32 s4, v251, 38
	s_add_i32 s4, s4, 8
	s_waitcnt lgkmcnt(0)
	s_cmp_ge_i32 s4, s7
	s_cbranch_scc1 .LBB0_2104
	s_waitcnt vmcnt(0)
	s_barrier
	s_mov_b64 s[16:17], exec
	v_readlane_b32 s6, v251, 22
	v_readlane_b32 s7, v251, 23
	s_and_b64 s[6:7], s[16:17], s[6:7]
	s_mov_b64 exec, s[6:7]
	s_cbranch_execz .LBB0_2103
	s_waitcnt vmcnt(0) lgkmcnt(0)
	v_mov_b32_e32 v2, 0x22020
	ds_read_b64 v[4:5], v2
	v_readlane_b32 s6, v252, 35
	v_readlane_b32 s7, v252, 36
	v_readlane_b32 s8, v252, 39
	v_readlane_b32 s9, v252, 40
	v_mov_b32_e32 v6, 1
	s_nop 4
	global_atomic_add v6, v3, v6, s[6:7] sc0
	s_waitcnt vmcnt(0) lgkmcnt(0)
	v_cvt_f32_u32_e32 v7, v6
	v_cvt_f32_u32_e32 v8, v4
	v_add_f32_e32 v7, 0.5, v7
	v_rcp_f32_e32 v8, v8
	s_nop 1
	v_mul_f32_e32 v7, v7, v8
	v_cvt_u32_f32_e32 v7, v7
	v_mad_u32_u24 v8, v7, v4, v4
	v_mad_u32_u24 v9, v7, v5, v5
	v_sub_u32_e32 v2, v8, v4
	v_cmp_ne_u32_e32 vcc, v6, v2
	s_cbranch_vccnz .Lxb_nf_6
	buffer_wbl2 sc1

.LBB0_2440:
	s_load_dwordx2 s[6:7], s[0:1], 0x150
	v_readlane_b32 s4, v251, 38
	s_add_i32 s4, s4, 9
	s_waitcnt lgkmcnt(0)
	s_cmp_ge_i32 s4, s7
	s_cbranch_scc1 .LBB0_2490
	s_waitcnt vmcnt(0)
	s_barrier
	s_mov_b64 s[16:17], exec
	v_readlane_b32 s6, v251, 22
	v_readlane_b32 s7, v251, 23
	s_and_b64 s[6:7], s[16:17], s[6:7]
	s_mov_b64 exec, s[6:7]
	s_cbranch_execz .LBB0_2489
	s_waitcnt vmcnt(0) lgkmcnt(0)
	v_mov_b32_e32 v2, 0x22020
	ds_read_b64 v[4:5], v2
	v_readlane_b32 s6, v252, 35
	v_readlane_b32 s7, v252, 36
	v_readlane_b32 s8, v252, 39
	v_readlane_b32 s9, v252, 40
	v_mov_b32_e32 v6, 1
	s_nop 4
	global_atomic_add v6, v3, v6, s[6:7] sc0
	s_waitcnt vmcnt(0) lgkmcnt(0)
	v_cvt_f32_u32_e32 v7, v6
	v_cvt_f32_u32_e32 v8, v4
	v_add_f32_e32 v7, 0.5, v7
	v_rcp_f32_e32 v8, v8
	s_nop 1
	v_mul_f32_e32 v7, v7, v8
	v_cvt_u32_f32_e32 v7, v7
	v_mad_u32_u24 v8, v7, v4, v4
	v_mad_u32_u24 v9, v7, v5, v5
	v_sub_u32_e32 v2, v8, v4
	v_cmp_ne_u32_e32 vcc, v6, v2
	s_cbranch_vccnz .Lxb_nf_7
	buffer_wbl2 sc1

.LBB0_2503:
	s_load_dwordx2 s[6:7], s[0:1], 0x150
	v_readlane_b32 s4, v251, 38
	s_add_i32 s4, s4, 10
	s_waitcnt lgkmcnt(0)
	s_cmp_ge_i32 s4, s7
	s_cbranch_scc1 .LBB0_2553
	s_waitcnt vmcnt(0)
	s_waitcnt vmcnt(0)
	s_barrier
	s_mov_b64 s[16:17], exec
	v_readlane_b32 s6, v251, 22
	v_readlane_b32 s7, v251, 23
	s_and_b64 s[6:7], s[16:17], s[6:7]
	s_mov_b64 exec, s[6:7]
	s_cbranch_execz .LBB0_2552
	s_waitcnt vmcnt(0) lgkmcnt(0)
	v_mov_b32_e32 v2, 0x22020
	ds_read_b64 v[4:5], v2
	v_readlane_b32 s6, v252, 35
	v_readlane_b32 s7, v252, 36
	v_readlane_b32 s8, v252, 39
	v_readlane_b32 s9, v252, 40
	v_mov_b32_e32 v6, 1
	s_nop 4
	global_atomic_add v6, v3, v6, s[6:7] sc0
	s_waitcnt vmcnt(0) lgkmcnt(0)
	v_cvt_f32_u32_e32 v7, v6
	v_cvt_f32_u32_e32 v8, v4
	v_add_f32_e32 v7, 0.5, v7
	v_rcp_f32_e32 v8, v8
	s_nop 1
	v_mul_f32_e32 v7, v7, v8
	v_cvt_u32_f32_e32 v7, v7
	v_mad_u32_u24 v8, v7, v4, v4
	v_mad_u32_u24 v9, v7, v5, v5
	v_sub_u32_e32 v2, v8, v4
	v_cmp_ne_u32_e32 vcc, v6, v2
	s_cbranch_vccnz .Lxb_nf_8
	buffer_wbl2 sc1

.LBB0_2909:
	s_load_dwordx2 s[6:7], s[0:1], 0x150
	v_readlane_b32 s4, v251, 38
	s_add_i32 s4, s4, 11
	s_waitcnt lgkmcnt(0)
	s_cmp_ge_i32 s4, s7
	s_cbranch_scc1 .LBB0_2959
	s_waitcnt vmcnt(0)
	s_waitcnt vmcnt(0)
	s_barrier
	s_mov_b64 s[16:17], exec
	v_readlane_b32 s6, v251, 22
	v_readlane_b32 s7, v251, 23
	s_and_b64 s[6:7], s[16:17], s[6:7]
	s_mov_b64 exec, s[6:7]
	s_cbranch_execz .LBB0_2958
	s_waitcnt vmcnt(0) lgkmcnt(0)
	v_mov_b32_e32 v2, 0x22020
	ds_read_b64 v[4:5], v2
	v_readlane_b32 s6, v252, 35
	v_readlane_b32 s7, v252, 36
	v_readlane_b32 s8, v252, 39
	v_readlane_b32 s9, v252, 40
	v_mov_b32_e32 v6, 1
	s_nop 4
	global_atomic_add v6, v3, v6, s[6:7] sc0
	s_waitcnt vmcnt(0) lgkmcnt(0)
	v_cvt_f32_u32_e32 v7, v6
	v_cvt_f32_u32_e32 v8, v4
	v_add_f32_e32 v7, 0.5, v7
	v_rcp_f32_e32 v8, v8
	s_nop 1
	v_mul_f32_e32 v7, v7, v8
	v_cvt_u32_f32_e32 v7, v7
	v_mad_u32_u24 v8, v7, v4, v4
	v_mad_u32_u24 v9, v7, v5, v5
	v_sub_u32_e32 v2, v8, v4
	v_cmp_ne_u32_e32 vcc, v6, v2
	s_cbranch_vccnz .Lxb_nf_9
	buffer_wbl2 sc1

.LBB0_2973:
	s_or_b64 exec, exec, s[16:17]
	s_load_dwordx2 s[6:7], s[0:1], 0x150
	v_readlane_b32 s4, v251, 38
	s_add_i32 s4, s4, 12
	s_waitcnt lgkmcnt(0)
	s_cmp_ge_i32 s4, s7
	s_cbranch_scc1 .LBB0_3023
	s_waitcnt vmcnt(0)
	s_barrier
	s_mov_b64 s[16:17], exec
	v_readlane_b32 s6, v251, 22
	v_readlane_b32 s7, v251, 23
	s_and_b64 s[6:7], s[16:17], s[6:7]
	s_mov_b64 exec, s[6:7]
	s_cbranch_execz .LBB0_3022
	s_waitcnt vmcnt(0) lgkmcnt(0)
	v_mov_b32_e32 v2, 0x22020
	ds_read_b64 v[4:5], v2
	v_readlane_b32 s6, v252, 35
	v_readlane_b32 s7, v252, 36
	v_readlane_b32 s8, v252, 39
	v_readlane_b32 s9, v252, 40
	v_mov_b32_e32 v6, 1
	s_nop 4
	global_atomic_add v6, v3, v6, s[6:7] sc0
	s_waitcnt vmcnt(0) lgkmcnt(0)
	v_cvt_f32_u32_e32 v7, v6
	v_cvt_f32_u32_e32 v8, v4
	v_add_f32_e32 v7, 0.5, v7
	v_rcp_f32_e32 v8, v8
	s_nop 1
	v_mul_f32_e32 v7, v7, v8
	v_cvt_u32_f32_e32 v7, v7
	v_mad_u32_u24 v8, v7, v4, v4
	v_mad_u32_u24 v9, v7, v5, v5
	v_sub_u32_e32 v2, v8, v4
	v_cmp_ne_u32_e32 vcc, v6, v2
	s_cbranch_vccnz .Lxb_nf_10
	buffer_wbl2 sc1

.LBB0_3055:
	s_waitcnt vmcnt(0) lgkmcnt(0)
	v_mov_b32_e32 v2, 0x22020
	ds_read_b64 v[4:5], v2
	v_readlane_b32 s6, v252, 35
	v_readlane_b32 s7, v252, 36
	v_readlane_b32 s8, v252, 39
	v_readlane_b32 s9, v252, 40
	v_mov_b32_e32 v6, 1
	s_nop 4
	global_atomic_add v6, v3, v6, s[6:7] sc0
	s_waitcnt vmcnt(0) lgkmcnt(0)
	v_cvt_f32_u32_e32 v7, v6
	v_cvt_f32_u32_e32 v8, v4
	v_add_f32_e32 v7, 0.5, v7
	v_rcp_f32_e32 v8, v8
	s_nop 1
	v_mul_f32_e32 v7, v7, v8
	v_cvt_u32_f32_e32 v7, v7
	v_mad_u32_u24 v8, v7, v4, v4
	v_mad_u32_u24 v9, v7, v5, v5
	v_sub_u32_e32 v2, v8, v4
	v_cmp_ne_u32_e32 vcc, v6, v2
	s_cbranch_vccnz .Lxb_nf_99
	buffer_wbl2 sc1
